# residual GEMM phases (FFN-out f0-f2, pool, O-proj) visit row-panel rounds in reverse so each ends on the rows the next phase starts with; V^T rounds reversed
# speedup vs baseline: 1.0283x; 1.0283x over previous
.LBB0_10:
	v_readlane_b32 s0, v254, 0
	s_cmp_le_i32 s75, s0
	s_cbranch_scc1 .LBB0_425
	s_add_u32 s76, s94, 0xa0
	s_addc_u32 s77, s95, 0
	s_lshl_b32 s98, s2, 3
	s_cmpk_lt_i32 s2, 0x400
	s_cselect_b64 s[96:97], -1, 0
	s_lshl_b32 s0, s2, 7
	v_writelane_b32 v254, s0, 1
	s_and_b32 s0, s0, 0x380
	s_ashr_i32 s1, s2, 3
	s_add_i32 s0, s0, s1
	s_ashr_i32 s4, s0, 2
	s_add_i32 s4, s4, 24
	s_lshl_b32 s0, s4, 8
	s_and_b32 s3, s1, 3
	v_writelane_b32 v254, s0, 2
	v_writelane_b32 v254, s3, 3
	s_lshl_b32 s0, s3, 19
	s_ashr_i32 s5, s4, 31
	v_writelane_b32 v254, s0, 4
	s_lshl_b64 s[6:7], s[4:5], 19
	v_writelane_b32 v254, s6, 5
	s_mov_b32 s0, s4
	s_ashr_i32 s5, s2, 31
	v_writelane_b32 v254, s7, 6
	v_writelane_b32 v254, s0, 7
	s_add_i32 s4, s4, -24
	s_and_b32 s3, s1, 7
	v_lshrrev_b32_e32 v1, 20, v0
	v_writelane_b32 v254, s1, 8
	s_and_b32 s0, s4, -8
	s_or_b32 s12, s0, s3
	s_lshl_b32 s6, s12, 8
	s_ashr_i32 s13, s12, 31
	s_bfe_u32 s4, s1, 0x20003
	v_writelane_b32 v254, s6, 9
	s_lshl_b64 s[6:7], s[12:13], 19
	s_lshr_b32 s0, s1, 3
	v_writelane_b32 v254, s6, 10
	s_mov_b32 s13, s4
	s_lshl_b32 s4, s4, 19
	v_writelane_b32 v254, s7, 11
	s_cmpk_lt_i32 s2, 0x1600
	v_writelane_b32 v254, s4, 12
	s_cselect_b64 s[6:7], -1, 0
	v_writelane_b32 v254, s6, 13
	s_add_i32 s4, s1, 0xfffffd80
	s_lshr_b32 s4, s4, 1
	v_writelane_b32 v254, s7, 14
	s_lshr_b32 s6, s1, 2
	s_ashr_i32 s7, s2, 8
	s_lshl_b32 s8, s2, 5
	s_and_b32 s4, s4, 0x7ffffff8
	s_and_b32 s6, s6, 24
	s_and_b32 s7, s7, -4
	s_and_b32 s8, s8, 0xe0
	s_add_i32 s9, s2, 1
	s_cmpk_lt_i32 s1, 0x280
	v_lshrrev_b32_e32 v0, 10, v0
	v_or_b32_e32 v0, v0, v1
	s_movk_i32 s1, 0x3ff
	s_cselect_b32 s4, s6, s4
	v_and_or_b32 v0, v0, s1, v190
	s_cselect_b32 s1, 3, 1
	s_cselect_b32 s7, s7, 20
	s_or_b32 s3, s4, s3
	s_and_b32 s0, s1, s0
	s_add_i32 s8, s3, s8
	v_writelane_b32 v254, s9, 15
	s_or_b32 s6, s0, s7
	s_lshl_b32 s0, s8, 8
	v_writelane_b32 v254, s0, 16
	s_lshl_b32 s0, s2, 1
	v_writelane_b32 v254, s0, 17
	s_lshl_b32 s0, s2, 12
	v_writelane_b32 v254, s0, 18
	s_lshl_b32 s0, s2, 6
	v_writelane_b32 v254, s0, 19
	s_lshl_b32 s0, s2, 8
	v_writelane_b32 v254, s0, 20
	s_lshl_b32 s0, s2, 9
	v_writelane_b32 v254, s0, 21
	s_add_i32 s0, s98, 0xd400
	v_writelane_b32 v254, s0, 22
	s_add_i32 s0, 0, 0x21004
	v_writelane_b32 v254, s0, 23
	v_cmp_eq_u32_e64 s[10:11], 0, v190
	v_readlane_b32 s0, v254, 0
	s_mov_b32 s51, 0
	v_writelane_b32 v254, s10, 24
	s_mov_b32 s4, s8
	s_mov_b32 s9, s51
	v_writelane_b32 v254, s11, 25
	v_cmp_eq_u32_e64 s[10:11], 0, v0
	s_lshl_b64 s[8:9], s[8:9], 19
	s_ashr_i32 s7, s6, 31
	v_writelane_b32 v254, s10, 26
	v_mbcnt_lo_u32_b32 v1, -1, 0
	s_movk_i32 s61, 0x1600
	v_writelane_b32 v254, s11, 27
	v_writelane_b32 v254, s4, 28
	s_movk_i32 s99, 0x1000
	v_mov_b32_e32 v49, 0
	v_writelane_b32 v254, s5, 29
	v_writelane_b32 v254, s8, 30
	s_mov_b32 s4, s6
	s_lshl_b64 s[6:7], s[6:7], 19
	v_writelane_b32 v254, s9, 31
	v_writelane_b32 v254, s4, 32
	s_mov_b32 s91, 0x10000
	s_add_i32 s62, 0, 0x10000
	v_writelane_b32 v254, s5, 33
	v_writelane_b32 v254, s6, 34
	s_mov_b32 s4, s12
	s_movk_i32 s88, 0x2000
	v_writelane_b32 v254, s7, 35
	v_writelane_b32 v254, s4, 36
	s_add_i32 s4, s4, 24
	v_writelane_b32 v254, s4, 61
	s_movk_i32 s90, 0x4000
	s_movk_i32 s84, 0x6000
	s_mov_b32 s85, 0x8000
	s_mov_b32 s89, 0xc000
	v_mov_b32_e32 v191, 0x358637bd
	s_mov_b32 s65, 0x5000000
	s_mov_b32 s66, 0xd000000
	s_mov_b32 s63, 0x40000
	s_mov_b32 s64, 0x48000
	v_mov_b32_e32 v226, 0x2000
	v_mov_b32_e32 v227, 1
	v_mov_b64_e32 v[192:193], 0x400
	v_mov_b64_e32 v[194:195], 0x3ff
	v_mbcnt_hi_u32_b32 v228, -1, v1
	v_mov_b64_e32 v[196:197], 0x15ff
	v_mov_b32_e32 v229, 0x108
	v_mov_b32_e32 v230, 0x420
	v_mov_b32_e32 v231, 0x840
	v_mov_b32_e32 v232, 0xc60
	v_mov_b32_e32 v233, 0x1080
	v_mov_b32_e32 v234, 0x14a0
	v_mov_b32_e32 v235, 0x18c0
	s_mov_b32 s67, 0x50000
	s_mov_b32 s57, 0xd001000
	s_mov_b32 s59, 0xd002000
	s_mov_b32 s43, 0xd003000
	s_movk_i32 s58, 0x5800
	s_mov_b64 s[70:71], 0x80
	v_writelane_b32 v254, s5, 37
	v_writelane_b32 v254, s13, 38
	s_branch .LBB0_14

.LBB0_180:
	s_cmp_eq_u32 s47, 13
	s_cselect_b64 s[12:13], -1, 0
	s_and_b64 s[0:1], s[12:13], exec
	s_cselect_b32 s4, 0x4c00000, s8
	s_cmp_eq_u32 s47, 4
	s_cselect_b64 s[10:11], -1, 0
	s_and_b64 s[0:1], s[10:11], exec
	s_mov_b32 s0, 0x15000000
	s_cselect_b32 s8, 0x5000000, s0
	s_cselect_b32 s4, 0x4e00000, s4
	s_or_b64 s[0:1], s[10:11], s[12:13]
	s_waitcnt lgkmcnt(0)
	s_add_u32 s36, s78, s8
	s_addc_u32 s37, s79, 0
	s_and_b64 s[14:15], s[0:1], exec
	s_cselect_b32 s8, 0, s9
	s_add_u32 s38, s78, s4
	s_addc_u32 s39, s79, s8
	s_and_b64 s[0:1], s[0:1], exec
	s_movk_i32 s0, 0xb00
	s_cselect_b32 s40, 0x400, s0
	s_cmp_eq_u32 s47, 10
	s_cselect_b64 s[0:1], -1, 0
	s_or_b64 s[8:9], s[10:11], s[0:1]
	s_cmp_eq_u32 s47, 15
	s_cselect_b64 s[0:1], -1, 0
	s_or_b64 s[0:1], s[0:1], s[8:9]
	s_and_b64 s[0:1], s[0:1], exec
	s_cselect_b32 s0, s66, 0x5000000
	s_add_u32 s16, s78, s0
	s_addc_u32 s17, s79, 0
	s_cmp_lg_u32 s47, 15
	s_mov_b64 s[14:15], -1
	s_cbranch_scc0 .LBB0_206
	s_and_b64 vcc, exec, s[6:7]
	v_readfirstlane_b32 s0, v237
	s_cbranch_vccnz .LBB0_205
	v_lshlrev_b32_e32 v238, 4, v237
	v_add_u32_e32 v0, 0x2000, v238
	v_ashrrev_i32_e32 v1, 31, v0
	v_lshrrev_b32_e32 v1, 22, v1
	v_add_u32_e32 v1, v0, v1
	v_ashrrev_i32_e32 v1, 10, v1
	v_mul_i32_i24_e32 v2, 0x400, v1
	v_sub_u32_e32 v0, v0, v2
	v_lshrrev_b32_e32 v2, 4, v0
	v_bitop3_b32 v0, v2, v0, 32 bitop3:0x6c
	s_and_b64 s[12:13], s[12:13], exec
	s_movk_i32 s1, 0xb00
	v_ashrrev_i32_e32 v2, 31, v0
	s_cselect_b32 s1, 0x400, s1
	s_and_b64 s[12:13], s[10:11], exec
	v_lshrrev_b32_e32 v2, 26, v2
	s_cselect_b32 s4, 0x100, s1
	s_ashr_i32 s12, s0, 6
	v_add_u32_e32 v2, v0, v2
	v_lshlrev_b32_e32 v4, 3, v1
	s_ashr_i32 s1, s0, 8
	s_lshl_b32 s50, s40, 8
	s_lshl_b32 s41, s4, 8
	s_lshl_b32 s48, s40, 9
	s_lshl_b32 s49, s4, 9
	s_lshl_b32 s52, s12, 10
	v_ashrrev_i32_e32 v3, 6, v2
	v_and_b32_e32 v4, -16, v4
	v_lshlrev_b32_e32 v1, 5, v1
	s_and_b64 s[10:11], s[10:11], exec
	v_add_u32_e32 v4, v3, v4
	v_and_b32_e32 v142, 32, v1
	v_and_b32_e32 v1, 0xc0, v2
	v_and_b32_e32 v3, 3, v3
	s_mov_b32 s10, 0xffffe0
	v_lshrrev_b32_e32 v5, 2, v4
	v_lshlrev_b32_e32 v6, 1, v4
	v_sub_u32_e32 v0, v0, v1
	v_and_or_b32 v3, v4, s10, v3
	v_and_b32_e32 v5, 4, v5
	v_and_b32_e32 v6, 24, v6
	v_ashrrev_i16_sdwa v0, v227, sext(v0) dst_sel:DWORD dst_unused:UNUSED_PAD src0_sel:DWORD src1_sel:BYTE_0
	v_or3_b32 v3, v3, v5, v6
	v_bfe_i32 v143, v0, 0, 16
	v_mul_u32_u24_e32 v3, s4, v3
	v_add_u32_e32 v0, v142, v143
	v_mul_lo_u32 v144, v4, s40
	v_add_lshl_u32 v198, v3, v0, 1
	v_add_lshl_u32 v200, v0, v144, 1
	v_bfe_i32 v0, v237, 27, 1
	v_lshrrev_b32_e32 v0, 22, v0
	v_add_u32_e32 v0, v238, v0
	v_and_b32_e32 v0, 0xfffffc00, v0
	v_sub_u32_e32 v0, v238, v0
	v_lshrrev_b32_e32 v1, 4, v0
	v_ashrrev_i32_e32 v3, 31, v237
	v_bitop3_b32 v0, v1, v0, 32 bitop3:0x6c
	v_lshrrev_b32_e32 v3, 26, v3
	v_ashrrev_i32_e32 v1, 31, v0
	v_add_u32_e32 v3, v237, v3
	v_lshrrev_b32_e32 v1, 26, v1
	v_ashrrev_i32_e32 v3, 6, v3
	v_add_u32_e32 v1, v0, v1
	v_lshlrev_b32_e32 v4, 3, v3
	v_ashrrev_i32_e32 v2, 6, v1
	v_and_b32_e32 v4, -16, v4
	v_add_u32_e32 v4, v2, v4
	v_and_b32_e32 v2, 3, v2
	v_and_or_b32 v2, v4, s10, v2
	v_readlane_b32 s10, v254, 61
	v_and_b32_e32 v1, 0xc0, v1
	v_readlane_b32 s11, v254, 37
	s_mov_b32 s14, s10
	s_cselect_b32 s53, 0x200, 0
	v_lshrrev_b32_e32 v5, 2, v4
	v_lshlrev_b32_e32 v6, 1, v4
	v_sub_u32_e32 v0, v0, v1
	s_mul_i32 s11, s48, s14
	v_readlane_b32 s14, v254, 38
	v_and_b32_e32 v5, 4, v5
	v_and_b32_e32 v6, 24, v6
	v_lshlrev_b32_e32 v3, 5, v3
	v_ashrrev_i16_sdwa v0, v227, sext(v0) dst_sel:DWORD dst_unused:UNUSED_PAD src0_sel:DWORD src1_sel:BYTE_0
	s_mul_i32 s13, s53, s14
	s_mul_i32 s14, s49, s14
	v_or3_b32 v2, v2, v5, v6
	v_and_b32_e32 v145, 32, v3
	v_bfe_i32 v146, v0, 0, 16
	s_add_u32 s30, s38, s14
	v_mul_u32_u24_e32 v2, s4, v2
	v_add_u32_e32 v0, v145, v146
	s_addc_u32 s31, s39, 0
	s_add_i32 s82, s52, 0
	v_add_lshl_u32 v48, v2, v0, 1
	v_mul_lo_u32 v147, v4, s40
	s_add_i32 m0, s82, 0x10000
	v_add_lshl_u32 v202, v0, v147, 1
	v_mov_b64 v[126:127], 0
	v_mov_b64 v[128:129], 0
	v_mov_b64 v[122:123], 0
	v_mov_b64 v[124:125], 0
	v_mov_b64 v[110:111], 0
	v_mov_b64 v[112:113], 0
	v_mov_b64 v[98:99], 0
	v_mov_b64 v[100:101], 0
	v_mov_b64 v[94:95], 0
	v_mov_b64 v[96:97], 0
	v_mov_b64 v[82:83], 0
	v_mov_b64 v[84:85], 0
	v_mov_b64 v[78:79], 0
	v_mov_b64 v[80:81], 0
	v_mov_b64 v[66:67], 0
	v_mov_b64 v[68:69], 0
	v_mov_b64 v[118:119], 0
	v_mov_b64 v[120:121], 0
	v_mov_b64 v[114:115], 0
	v_mov_b64 v[116:117], 0
	v_mov_b64 v[106:107], 0
	v_mov_b64 v[108:109], 0
	v_mov_b64 v[102:103], 0
	v_mov_b64 v[104:105], 0
	v_mov_b64 v[90:91], 0
	v_mov_b64 v[92:93], 0
	v_mov_b64 v[86:87], 0
	v_mov_b64 v[88:89], 0
	v_mov_b64 v[74:75], 0
	v_mov_b64 v[76:77], 0
	v_mov_b64 v[70:71], 0
	v_mov_b64 v[72:73], 0
	v_mov_b64 v[62:63], 0
	v_mov_b64 v[64:65], 0
	v_mov_b64 v[50:51], 0
	v_mov_b64 v[52:53], 0
	v_mov_b64 v[44:45], 0
	v_mov_b64 v[46:47], 0
	v_mov_b64 v[32:33], 0
	v_mov_b64 v[34:35], 0
	v_mov_b64 v[28:29], 0
	v_mov_b64 v[30:31], 0
	v_mov_b64 v[16:17], 0
	v_mov_b64 v[18:19], 0
	v_mov_b64 v[12:13], 0
	v_mov_b64 v[14:15], 0
	v_mov_b64 v[0:1], 0
	v_mov_b64 v[2:3], 0
	v_mov_b64 v[58:59], 0
	v_mov_b64 v[60:61], 0
	v_mov_b64 v[54:55], 0
	v_mov_b64 v[56:57], 0
	v_mov_b64 v[40:41], 0
	v_mov_b64 v[42:43], 0
	v_mov_b64 v[36:37], 0
	v_mov_b64 v[38:39], 0
	v_mov_b64 v[24:25], 0
	v_mov_b64 v[26:27], 0
	v_mov_b64 v[20:21], 0
	v_mov_b64 v[22:23], 0
	v_mov_b64 v[8:9], 0
	v_mov_b64 v[10:11], 0
	v_mov_b64 v[4:5], 0
	v_mov_b64 v[6:7], 0
	global_load_lds_dwordx4 v48, s[30:31]
	s_add_i32 m0, s82, 0x12000
	s_mul_hi_i32 s10, s48, s10
	s_add_u32 s14, s36, s11
	s_addc_u32 s15, s37, s10
	s_add_u32 s10, s30, s41
	global_load_lds_dwordx4 v198, s[30:31]
	s_addc_u32 s11, s31, 0
	s_add_i32 m0, s82, 0x14000
	v_mov_b32_e32 v199, v49
	global_load_lds_dwordx4 v48, s[10:11]
	s_add_i32 m0, s82, 0x16000
	s_add_u32 s34, s14, s13
	s_addc_u32 s35, s15, 0
	s_add_i32 s83, s82, 0x2000
	v_lshl_add_u64 v[134:135], s[10:11], 0, v[48:49]
	v_lshl_add_u64 v[136:137], s[10:11], 0, v[198:199]
	global_load_lds_dwordx4 v198, s[10:11]
	s_mov_b32 m0, s82
	s_add_u32 s10, s34, s50
	global_load_lds_dwordx4 v202, s[34:35]
	s_mov_b32 m0, s83
	s_addc_u32 s11, s35, 0
	s_add_i32 s84, s82, 0x4000
	global_load_lds_dwordx4 v200, s[34:35]
	s_mov_b32 m0, s84
	s_add_i32 s85, s82, 0x6000
	global_load_lds_dwordx4 v202, s[10:11]
	s_mov_b32 m0, s85
	v_mov_b32_e32 v203, v49
	global_load_lds_dwordx4 v200, s[10:11]
	v_mov_b32_e32 v201, v49
	s_cmp_eq_u32 s1, 1
	s_mov_b32 s54, s86
	v_lshl_add_u64 v[130:131], s[30:31], 0, v[48:49]
	v_lshl_add_u64 v[132:133], s[30:31], 0, v[198:199]
	v_lshl_add_u64 v[138:139], s[34:35], 0, v[202:203]
	v_lshl_add_u64 v[140:141], s[34:35], 0, v[200:201]
	s_cselect_b64 s[18:19], -1, 0
	s_cmp_lg_u32 s1, 1
	s_cbranch_scc1 .LBB0_184
	s_barrier
.LBB0_184:
	s_and_b64 s[10:11], s[8:9], exec
	s_cselect_b32 s10, 0x5000000, s66
	s_add_u32 s20, s78, s10
	s_addc_u32 s21, s79, 0
	s_and_b64 s[8:9], s[8:9], exec
	s_cselect_b32 s8, 0, 0x100000
	s_add_u32 s22, s78, s8
	s_addc_u32 s23, s79, 0
	s_add_i32 m0, s82, 0x18000
	v_lshl_add_u64 v[130:131], v[130:131], 0, s[70:71]
	s_waitcnt vmcnt(2)
	s_barrier
	global_load_lds_dwordx4 v[130:131], off
	v_lshl_add_u64 v[130:131], v[132:133], 0, s[70:71]
	s_add_i32 m0, s82, 0x1a000
	s_add_i32 s86, s82, 0x8000
	global_load_lds_dwordx4 v[130:131], off
	v_lshl_add_u64 v[130:131], v[138:139], 0, s[70:71]
	s_mov_b32 m0, s86
	s_add_i32 s87, s82, 0xa000
	global_load_lds_dwordx4 v[130:131], off
	v_lshl_add_u64 v[130:131], v[140:141], 0, s[70:71]
	s_mov_b32 m0, s87
	s_and_b32 s10, s12, 3
	global_load_lds_dwordx4 v[130:131], off
	s_add_i32 m0, s82, 0x1c000
	v_lshl_add_u64 v[130:131], v[134:135], 0, s[70:71]
	global_load_lds_dwordx4 v[130:131], off
	v_lshl_add_u64 v[130:131], v[136:137], 0, s[70:71]
	s_add_i32 m0, s82, 0x1e000
	v_lshlrev_b32_e32 v134, 2, v237
	global_load_lds_dwordx4 v[130:131], off
	v_bfe_u32 v130, v237, 4, 2
	v_and_b32_e32 v131, 15, v237
	v_lshlrev_b32_e32 v133, 4, v130
	s_lshr_b32 s89, s4, 6
	s_lshl_b32 s4, s1, 6
	v_lshl_or_b32 v133, v131, 6, v133
	s_lshl_b32 s1, s1, 13
	v_and_b32_e32 v134, 32, v134
	v_bitop3_b32 v135, v133, s1, v134 bitop3:0xde
	s_lshl_b32 s1, s10, 12
	s_add_i32 s90, s89, -2
	s_cmpk_lt_u32 s0, 0x100
	v_bitop3_b32 v240, s1, v133, v134 bitop3:0xf6
	s_cselect_b64 s[24:25], -1, 0
	s_add_i32 s1, s4, 0x80
	v_lshlrev_b32_e32 v132, 3, v130
	v_cmp_eq_u32_e64 s[8:9], 0, v130
	v_or_b32_e32 v130, s1, v131
	s_add_i32 s1, s4, 0x90
	v_lshlrev_b32_e32 v133, 4, v130
	v_or_b32_e32 v130, s1, v131
	s_add_i32 s1, s4, 0xa0
	v_or_b32_e32 v239, s4, v131
	v_lshlrev_b32_e32 v134, 4, v130
	v_or_b32_e32 v130, s1, v131
	s_addk_i32 s4, 0xb0
	v_lshlrev_b32_e32 v136, 4, v130
	v_or_b32_e32 v130, s4, v131
	s_lshl_b32 s0, s10, 2
	v_lshlrev_b32_e32 v137, 4, v130
	v_add_u32_e32 v130, v147, v145
	s_add_i32 s0, s0, 0
	v_add_lshl_u32 v130, v130, v146, 1
	v_mov_b32_e32 v131, v49
	s_waitcnt vmcnt(6)
	v_lshl_or_b32 v241, s10, 5, v132
	s_add_i32 s0, s0, 0x20000
	v_lshlrev_b32_e32 v132, 4, v239
	v_lshl_add_u64 v[204:205], s[50:51], 0, v[130:131]
	v_add_u32_e32 v130, v144, v142
	s_movk_i32 s1, 0x100
	v_add_lshl_u32 v130, v130, v143, 1
	v_add_u32_e32 v243, s0, v132
	v_add_u32_e32 v244, s0, v133
	v_add_u32_e32 v245, s0, v134
	v_add_u32_e32 v246, s0, v136
	v_add_u32_e32 v247, s0, v137
	v_readlane_b32 s0, v254, 38
	s_mov_b32 s88, 0
	v_cmp_gt_i32_e64 s[10:11], s1, v237
	s_ashr_i32 s91, s3, 31
	v_lshl_add_u64 v[206:207], s[50:51], 0, v[130:131]
	v_add_u32_e32 v242, 0, v135
	s_mov_b32 s26, s0
	v_readlane_b32 s0, v254, 61
	s_barrier
	v_readlane_b32 s1, v254, 37
	s_branch .LBB0_187

.LBB0_187:
	s_add_i32 s88, s88, 1
	s_mul_i32 s1, s88, s91
	s_mul_hi_u32 s4, s88, s3
	s_add_i32 s4, s4, s1
	s_mul_i32 s1, s88, s3
	s_add_u32 s12, s1, s2
	s_addc_u32 s13, s4, s5
	v_cmp_gt_i64_e32 vcc, s[12:13], v[194:195]
	v_cmp_lt_i64_e64 s[14:15], s[12:13], v[192:193]
	s_cbranch_vccnz .LBB0_189
	s_lshl_b32 s1, s12, 7
	s_and_b32 s1, s1, 0x380
	s_ashr_i32 s4, s12, 3
	s_xor_b32 s4, s4, 0x60
	s_add_i32 s1, s1, s4
	s_ashr_i32 s1, s1, 2
	s_and_b32 s1, s1, -8
	s_and_b32 s12, s4, 7
	s_or_b32 s93, s1, s12
	s_bfe_u32 s92, s4, 0x20003
